# attention steady loop: V-fragment base address VALU hoisted above the step barriers (segment heads start with LDS reads)
# speedup vs baseline: 1.0051x; 1.0006x over previous
.Lrot_body:
	v_add_u32_e32 v214, s20, v251
.Lrot_body2:
	ds_read_b64_tr_b16 v[208:209], v214 offset:24576
	ds_read_b64_tr_b16 v[210:211], v214 offset:25088
	s_waitcnt lgkmcnt(9)
	v_mfma_f32_32x32x16_bf16 v[128:143], v[204:207], v[172:175], v[226:241]
	v_add_f32_e32 v2, v96, v97
	v_add_f32_e32 v2, v98, v2
	v_add_f32_e32 v2, v99, v2
	v_add_f32_e32 v2, v100, v2
	v_add_f32_e32 v2, v101, v2
	v_cvt_pk_bf16_f32 v160, v96, v97
	v_cvt_pk_bf16_f32 v161, v98, v99
	ds_read_b64_tr_b16 v[204:205], v214 offset:28672
	ds_read_b64_tr_b16 v[206:207], v214 offset:29184
	s_waitcnt lgkmcnt(10)
	v_mfma_f32_32x32x16_bf16 v[112:127], v[196:199], v[172:175], v[226:241]
	v_add_f32_e32 v2, v102, v2
	v_add_f32_e32 v2, v103, v2
	v_add_f32_e32 v2, v104, v2
	v_add_f32_e32 v2, v105, v2
	v_cvt_pk_bf16_f32 v162, v100, v101
	v_cvt_pk_bf16_f32 v163, v102, v103
	ds_read_b64_tr_b16 v[10:11], v214 offset:25600
	ds_read_b64_tr_b16 v[12:13], v214 offset:26112
	s_waitcnt lgkmcnt(11)
	v_mfma_f32_32x32x16_bf16 v[128:143], v[200:203], v[168:171], v[128:143]
	v_add_f32_e32 v2, v106, v2
	v_add_f32_e32 v2, v107, v2
	v_add_f32_e32 v2, v108, v2
	v_add_f32_e32 v2, v109, v2
	v_cvt_pk_bf16_f32 v152, v104, v105
	v_cvt_pk_bf16_f32 v153, v106, v107
	ds_read_b64_tr_b16 v[6:7], v214 offset:29696
	ds_read_b64_tr_b16 v[8:9], v214 offset:30208
	s_waitcnt lgkmcnt(12)
	v_mfma_f32_32x32x16_bf16 v[112:127], v[192:195], v[168:171], v[112:127]
	v_add_f32_e32 v2, v110, v2
	v_add_f32_e32 v2, v111, v2
	v_add_f32_e32 v2, v80, v2
	v_add_f32_e32 v14, v81, v2
	v_cvt_pk_bf16_f32 v154, v108, v109
	v_cvt_pk_bf16_f32 v155, v110, v111
	ds_read_b64_tr_b16 v[2:3], v214 offset:26624
	ds_read_b64_tr_b16 v[4:5], v214 offset:27136
	s_waitcnt lgkmcnt(13)
	v_mfma_f32_32x32x16_bf16 v[128:143], v[188:191], v[164:167], v[128:143]
	v_add_f32_e32 v14, v82, v14
	v_add_f32_e32 v14, v83, v14
	v_add_f32_e32 v14, v84, v14
	v_add_f32_e32 v14, v85, v14
	v_cvt_pk_bf16_f32 v148, v80, v81
	v_cvt_pk_bf16_f32 v149, v82, v83
	ds_read_b64_tr_b16 v[100:101], v214 offset:30720
	ds_read_b64_tr_b16 v[102:103], v214 offset:31232
	s_waitcnt lgkmcnt(14)
	v_mfma_f32_32x32x16_bf16 v[112:127], v[184:187], v[164:167], v[112:127]
	v_add_f32_e32 v14, v86, v14
	v_add_f32_e32 v14, v87, v14
	v_add_f32_e32 v14, v88, v14
	v_add_f32_e32 v14, v89, v14
	v_cvt_pk_bf16_f32 v150, v84, v85
	v_cvt_pk_bf16_f32 v151, v86, v87
	ds_read_b64_tr_b16 v[96:97], v214 offset:27648
	ds_read_b64_tr_b16 v[98:99], v214 offset:28160
	s_waitcnt lgkmcnt(14)
	v_mfma_f32_32x32x16_bf16 v[128:143], v[180:183], v[156:159], v[128:143]
	v_add_f32_e32 v14, v90, v14
	v_add_f32_e32 v14, v91, v14
	v_add_f32_e32 v14, v92, v14
	v_add_f32_e32 v14, v93, v14
	v_cvt_pk_bf16_f32 v144, v88, v89
	v_cvt_pk_bf16_f32 v145, v90, v91
	ds_read_b64_tr_b16 v[88:89], v214 offset:31744
	ds_read_b64_tr_b16 v[90:91], v214 offset:32256
	v_mfma_f32_32x32x16_bf16 v[112:127], v[176:179], v[156:159], v[112:127]
	v_add_f32_e32 v14, v94, v14
	v_add_f32_e32 v14, v95, v14
	v_add_f32_e32 v212, v247, v14
	v_cvt_pk_bf16_f32 v146, v92, v93
	v_cvt_pk_bf16_f32 v147, v94, v95
	s_add_u32 s30, s2, s78
	s_addc_u32 s31, s3, s79
	v_lshl_add_u64 v[80:81], v[220:221], 0, s[30:31]
	s_add_i32 s20, s29, s48


	s_mov_b32 s21, m0
	s_mov_b32 m0, s20
	s_nop 0
	global_load_lds_dwordx4 v[80:81], off
	s_mov_b32 m0, s21
	s_add_u32 s30, s2, 0x40000
	s_addc_u32 s31, s3, 0
	v_lshl_add_u64 v[80:81], v[222:223], 0, s[30:31]
	s_lshl_b32 s20, s27, 1

	s_add_i32 s21, s20, s49
	s_mov_b32 s24, m0
	s_mov_b32 m0, s21
	s_nop 0
	global_load_lds_dwordx4 v[80:81], off
	s_mov_b32 m0, s24
	v_lshl_add_u64 v[80:81], v[224:225], 0, s[30:31]
	s_add_i32 s20, s20, s50
	s_mov_b32 s21, m0
	s_mov_b32 m0, s20
	s_nop 0
	global_load_lds_dwordx4 v[80:81], off
	s_mov_b32 m0, s21
	v_max_f32_e32 v80, v128, v129


	v_max3_f32 v81, v130, v131, v113
	v_max3_f32 v80, v80, v112, v114
	v_max3_f32 v80, v80, v115, v132
	v_max3_f32 v81, v81, v134, v135
	v_max3_f32 v80, v80, v133, v116
	v_max3_f32 v81, v81, v118, v119
	v_max3_f32 v80, v80, v117, v136
	v_max3_f32 v81, v81, v138, v139
	v_max3_f32 v80, v80, v137, v120
	v_max3_f32 v81, v81, v122, v123
	v_max3_f32 v80, v80, v121, v140
	v_max3_f32 v81, v81, v142, v143
	v_max3_f32 v80, v80, v141, v124
	v_max3_f32 v81, v81, v126, v127
	v_max3_f32 v80, v80, v125, v81
	v_mov_b32_e32 v81, v80
	s_nop 1
	v_permlane32_swap_b32_e32 v80, v81
	v_max_f32_e32 v80, v80, v81


	s_mov_b32 s20, 0x41000000
	v_cmp_lt_f32_e32 vcc, s20, v80
	s_cmp_lg_u64 vcc, 0

	s_cselect_b64 s[20:21], -1, 0
	s_cbranch_vccnz .LBB0_1997
.LBB0_1990:
	s_waitcnt lgkmcnt(14)
	v_mfma_f32_32x32x16_bf16 v[64:79], v[160:163], v[208:211], v[64:79]
	v_exp_f32_e32 v128, v128
	v_exp_f32_e32 v129, v129
	ds_read_b64_tr_b16 v[92:93], v214 offset:32768
	ds_read_b64_tr_b16 v[94:95], v214 offset:33280
	s_waitcnt lgkmcnt(14)
	v_mfma_f32_32x32x16_bf16 v[48:63], v[160:163], v[204:207], v[48:63]
	v_exp_f32_e32 v130, v130
	v_exp_f32_e32 v131, v131
	ds_read_b64_tr_b16 v[104:105], v214 offset:36864
	ds_read_b64_tr_b16 v[106:107], v214 offset:37376
	v_add_u32_e32 v196, s27, v250
	ds_read_b128 v[84:87], v196
	ds_read_b128 v[80:83], v196 offset:512
	s_waitcnt lgkmcnt(14)
	v_mfma_f32_32x32x16_bf16 v[64:79], v[152:155], v[10:13], v[64:79]
	v_exp_f32_e32 v132, v132
	v_exp_f32_e32 v133, v133
	ds_read_b64_tr_b16 v[108:109], v214 offset:33792
	ds_read_b64_tr_b16 v[110:111], v214 offset:34304
	ds_read_b128 v[184:187], v196 offset:2048
	ds_read_b128 v[176:179], v196 offset:2560
	v_mfma_f32_32x32x16_bf16 v[48:63], v[152:155], v[6:9], v[48:63]
	v_exp_f32_e32 v134, v134
	v_exp_f32_e32 v135, v135
	ds_read_b64_tr_b16 v[188:189], v214 offset:37888
	ds_read_b64_tr_b16 v[190:191], v214 offset:38400
	ds_read_b128 v[180:183], v196 offset:4096
	ds_read_b128 v[6:9], v196 offset:4608
	s_waitcnt lgkmcnt(14)
	v_mfma_f32_32x32x16_bf16 v[64:79], v[148:151], v[2:5], v[64:79]
	v_exp_f32_e32 v136, v136
	v_exp_f32_e32 v137, v137
	ds_read_b64_tr_b16 v[192:193], v214 offset:34816
	ds_read_b64_tr_b16 v[194:195], v214 offset:35328
	ds_read_b128 v[10:13], v196 offset:6144
	ds_read_b128 v[2:5], v196 offset:6656
	v_mfma_f32_32x32x16_bf16 v[48:63], v[148:151], v[100:103], v[48:63]
	v_exp_f32_e32 v138, v138
	v_exp_f32_e32 v139, v139
	ds_read_b64_tr_b16 v[100:101], v214 offset:38912
	ds_read_b64_tr_b16 v[102:103], v214 offset:39424
	v_mfma_f32_32x32x16_bf16 v[64:79], v[144:147], v[96:99], v[64:79]
	v_exp_f32_e32 v140, v140
	v_exp_f32_e32 v141, v141
	ds_read_b64_tr_b16 v[96:97], v214 offset:35840
	ds_read_b64_tr_b16 v[98:99], v214 offset:36352
	v_mfma_f32_32x32x16_bf16 v[48:63], v[144:147], v[88:91], v[48:63]
	v_exp_f32_e32 v142, v142
	v_exp_f32_e32 v143, v143
	ds_read_b64_tr_b16 v[88:89], v214 offset:39936
	ds_read_b64_tr_b16 v[90:91], v214 offset:40448
	s_waitcnt lgkmcnt(14)
	v_mfma_f32_32x32x16_bf16 v[32:47], v[160:163], v[92:95], v[32:47]
	v_exp_f32_e32 v112, v112
	v_exp_f32_e32 v113, v113
	v_mfma_f32_32x32x16_bf16 v[16:31], v[160:163], v[104:107], v[16:31]
	v_exp_f32_e32 v114, v114
	v_exp_f32_e32 v115, v115
	v_mfma_f32_32x32x16_bf16 v[32:47], v[152:155], v[108:111], v[32:47]
	v_exp_f32_e32 v116, v116
	v_exp_f32_e32 v117, v117
	s_waitcnt lgkmcnt(12)
	v_mfma_f32_32x32x16_bf16 v[16:31], v[152:155], v[188:191], v[16:31]
	v_exp_f32_e32 v118, v118
	v_exp_f32_e32 v119, v119
	s_waitcnt lgkmcnt(8)
	v_mfma_f32_32x32x16_bf16 v[32:47], v[148:151], v[192:195], v[32:47]
	v_exp_f32_e32 v120, v120
	v_exp_f32_e32 v121, v121
	s_waitcnt lgkmcnt(4)
	v_mfma_f32_32x32x16_bf16 v[16:31], v[148:151], v[100:103], v[16:31]
	v_exp_f32_e32 v122, v122
	v_exp_f32_e32 v123, v123
	s_waitcnt lgkmcnt(2)
	v_mfma_f32_32x32x16_bf16 v[32:47], v[144:147], v[96:99], v[32:47]
	v_exp_f32_e32 v124, v124
	v_exp_f32_e32 v125, v125
	s_waitcnt lgkmcnt(0)
	v_mfma_f32_32x32x16_bf16 v[16:31], v[144:147], v[88:91], v[16:31]
	v_exp_f32_e32 v126, v126
	v_exp_f32_e32 v127, v127
	s_add_i32 s24, s27, 0x2000
	s_cmpk_lg_i32 s27, 0x4000
	s_cselect_b32 s52, s24, 0
	s_lshl_b32 s24, s29, 1
	v_add_u32_e32 v213, s24, v251
	v_add_u32_e32 v0, s46, v252
	s_waitcnt vmcnt(3) lgkmcnt(0)
	s_barrier
	s_andn2_b64 vcc, exec, s[20:21]

	s_cbranch_vccnz .LBB0_1992
	s_waitcnt lgkmcnt(0)
	ds_read_b128 v[88:91], v0 offset:96
	ds_read_b128 v[92:95], v0 offset:64
	ds_read_b128 v[96:99], v0 offset:32
	ds_read_b128 v[100:103], v0
	s_waitcnt lgkmcnt(3)
	v_mul_f32_e32 v76, v76, v88
	v_mul_f32_e32 v77, v77, v89
	s_waitcnt lgkmcnt(2)
	v_mul_f32_e32 v72, v72, v92
	v_mul_f32_e32 v73, v73, v93
	s_waitcnt lgkmcnt(1)
	v_mul_f32_e32 v68, v68, v96
	v_mul_f32_e32 v69, v69, v97
	v_mul_f32_e32 v78, v78, v90
	v_mul_f32_e32 v79, v79, v91
	v_mul_f32_e32 v74, v74, v94
	v_mul_f32_e32 v75, v75, v95
	v_mul_f32_e32 v70, v70, v98
	v_mul_f32_e32 v71, v71, v99
	s_waitcnt lgkmcnt(0)
	v_mul_f32_e32 v66, v66, v102
	v_mul_f32_e32 v67, v67, v103
	v_mul_f32_e32 v64, v64, v100
	v_mul_f32_e32 v65, v65, v101
	v_mul_f32_e32 v60, v60, v88
	v_mul_f32_e32 v61, v61, v89
	v_mul_f32_e32 v56, v56, v92
	v_mul_f32_e32 v57, v57, v93
	v_mul_f32_e32 v52, v52, v96
	v_mul_f32_e32 v53, v53, v97
	v_mul_f32_e32 v62, v62, v90
	v_mul_f32_e32 v63, v63, v91
	v_mul_f32_e32 v58, v58, v94
	v_mul_f32_e32 v59, v59, v95
	v_mul_f32_e32 v54, v54, v98
	v_mul_f32_e32 v55, v55, v99
	v_mul_f32_e32 v50, v50, v102
	v_mul_f32_e32 v51, v51, v103
	v_mul_f32_e32 v48, v48, v100
	v_mul_f32_e32 v49, v49, v101
	v_mul_f32_e32 v44, v44, v88
	v_mul_f32_e32 v45, v45, v89
	v_mul_f32_e32 v40, v40, v92
	v_mul_f32_e32 v41, v41, v93
	v_mul_f32_e32 v36, v36, v96
	v_mul_f32_e32 v37, v37, v97
	v_mul_f32_e32 v46, v46, v90
	v_mul_f32_e32 v47, v47, v91
	v_mul_f32_e32 v42, v42, v94
	v_mul_f32_e32 v43, v43, v95
	v_mul_f32_e32 v38, v38, v98
	v_mul_f32_e32 v39, v39, v99
	v_mul_f32_e32 v34, v34, v102
	v_mul_f32_e32 v35, v35, v103
	v_mul_f32_e32 v32, v32, v100
	v_mul_f32_e32 v33, v33, v101
	v_mul_f32_e32 v28, v28, v88
	v_mul_f32_e32 v29, v29, v89
	v_mul_f32_e32 v24, v24, v92
	v_mul_f32_e32 v25, v25, v93
	v_mul_f32_e32 v20, v20, v96
	v_mul_f32_e32 v21, v21, v97
	v_mul_f32_e32 v30, v30, v90
	v_mul_f32_e32 v31, v31, v91
	v_mul_f32_e32 v26, v26, v94
	v_mul_f32_e32 v27, v27, v95
	v_mul_f32_e32 v22, v22, v98
	v_mul_f32_e32 v23, v23, v99
	v_mul_f32_e32 v18, v18, v102
	v_mul_f32_e32 v19, v19, v103
	v_mul_f32_e32 v16, v16, v100
	v_mul_f32_e32 v17, v17, v101
.LBB0_1992:


	ds_read_b64_tr_b16 v[196:197], v213 offset:24576
	ds_read_b64_tr_b16 v[198:199], v213 offset:25088
	v_mfma_f32_32x32x16_bf16 v[96:111], v[84:87], v[172:175], v[226:241]
	v_add_f32_e32 v88, v128, v129
	v_add_f32_e32 v88, v130, v88
	v_add_f32_e32 v88, v131, v88
	v_add_f32_e32 v88, v132, v88
	v_add_f32_e32 v88, v133, v88
	v_cvt_pk_bf16_f32 v160, v128, v129
	v_cvt_pk_bf16_f32 v161, v130, v131
	ds_read_b64_tr_b16 v[192:193], v213 offset:28672
	ds_read_b64_tr_b16 v[194:195], v213 offset:29184
	v_add_f32_e32 v84, v134, v88
	v_add_f32_e32 v84, v135, v84
	v_add_f32_e32 v84, v136, v84
	v_add_f32_e32 v128, v137, v84
	v_mfma_f32_32x32x16_bf16 v[80:95], v[80:83], v[172:175], v[226:241]
	v_cvt_pk_bf16_f32 v162, v132, v133
	v_cvt_pk_bf16_f32 v163, v134, v135
	ds_read_b64_tr_b16 v[188:189], v213 offset:25600
	ds_read_b64_tr_b16 v[190:191], v213 offset:26112
	v_mfma_f32_32x32x16_bf16 v[96:111], v[184:187], v[168:171], v[96:111]
	v_add_f32_e32 v128, v138, v128
	v_add_f32_e32 v128, v139, v128
	v_add_f32_e32 v128, v140, v128
	v_add_f32_e32 v128, v141, v128
	v_cvt_pk_bf16_f32 v152, v136, v137
	v_cvt_pk_bf16_f32 v153, v138, v139
	ds_read_b64_tr_b16 v[136:137], v213 offset:29696
	ds_read_b64_tr_b16 v[138:139], v213 offset:30208
	v_mfma_f32_32x32x16_bf16 v[80:95], v[176:179], v[168:171], v[80:95]
	v_add_f32_e32 v128, v142, v128
	v_add_f32_e32 v128, v143, v128
	v_add_f32_e32 v128, v112, v128
	v_add_f32_e32 v128, v113, v128
	v_cvt_pk_bf16_f32 v154, v140, v141
	v_cvt_pk_bf16_f32 v155, v142, v143
	ds_read_b64_tr_b16 v[132:133], v213 offset:26624
	ds_read_b64_tr_b16 v[134:135], v213 offset:27136
	v_mfma_f32_32x32x16_bf16 v[96:111], v[180:183], v[164:167], v[96:111]
	v_add_f32_e32 v128, v114, v128
	v_add_f32_e32 v128, v115, v128
	v_add_f32_e32 v128, v116, v128
	v_add_f32_e32 v140, v117, v128
	v_cvt_pk_bf16_f32 v148, v112, v113
	v_cvt_pk_bf16_f32 v149, v114, v115
	ds_read_b64_tr_b16 v[128:129], v213 offset:30720
	ds_read_b64_tr_b16 v[130:131], v213 offset:31232
	v_mfma_f32_32x32x16_bf16 v[80:95], v[6:9], v[164:167], v[80:95]
	v_add_f32_e32 v6, v118, v140
	v_add_f32_e32 v6, v119, v6
	v_add_f32_e32 v6, v120, v6
	v_add_f32_e32 v6, v121, v6
	v_cvt_pk_bf16_f32 v150, v116, v117
	v_cvt_pk_bf16_f32 v151, v118, v119
	ds_read_b64_tr_b16 v[112:113], v213 offset:27648
	ds_read_b64_tr_b16 v[114:115], v213 offset:28160
	v_mfma_f32_32x32x16_bf16 v[96:111], v[10:13], v[156:159], v[96:111]
	v_add_f32_e32 v6, v122, v6
	v_add_f32_e32 v6, v123, v6
	v_add_f32_e32 v6, v124, v6
	v_add_f32_e32 v10, v125, v6
	v_cvt_pk_bf16_f32 v144, v120, v121
	v_cvt_pk_bf16_f32 v145, v122, v123
	ds_read_b64_tr_b16 v[6:7], v213 offset:31744
	ds_read_b64_tr_b16 v[8:9], v213 offset:32256
	v_mfma_f32_32x32x16_bf16 v[80:95], v[2:5], v[156:159], v[80:95]
	v_add_f32_e32 v2, v126, v10
	v_add_f32_e32 v2, v127, v2
	v_add_f32_e32 v247, v212, v2
	v_cvt_pk_bf16_f32 v146, v124, v125
	v_cvt_pk_bf16_f32 v147, v126, v127
	s_add_u32 s20, s2, 0xa0000
	s_addc_u32 s21, s3, 0
	v_lshl_add_u64 v[2:3], v[220:221], 0, s[20:21]
	s_add_i32 s20, s27, s48
	s_mov_b32 s21, m0
	s_mov_b32 m0, s20
	s_nop 0
	global_load_lds_dwordx4 v[2:3], off
	s_mov_b32 m0, s21
	s_add_u32 s30, s2, s56
	s_addc_u32 s31, s3, s57
	v_lshl_add_u64 v[2:3], v[222:223], 0, s[30:31]
	s_lshl_b32 s20, s52, 1
	s_add_i32 s21, s20, s49
	s_mov_b32 s24, m0
	s_mov_b32 m0, s21
	s_nop 0
	global_load_lds_dwordx4 v[2:3], off
	s_mov_b32 m0, s24
	v_lshl_add_u64 v[2:3], v[224:225], 0, s[30:31]
	s_add_i32 s20, s20, s50
	s_mov_b32 s21, m0
	s_mov_b32 m0, s20
	s_nop 0
	global_load_lds_dwordx4 v[2:3], off
	s_mov_b32 m0, s21
	v_max_f32_e32 v2, v96, v97


	v_max3_f32 v3, v98, v99, v81
	v_max3_f32 v2, v2, v80, v82
	v_max3_f32 v2, v2, v83, v100
	v_max3_f32 v3, v3, v102, v103
	v_max3_f32 v2, v2, v101, v84
	v_max3_f32 v3, v3, v86, v87
	v_max3_f32 v2, v2, v85, v104
	v_max3_f32 v3, v3, v106, v107
	v_max3_f32 v2, v2, v105, v88
	v_max3_f32 v3, v3, v90, v91
	v_max3_f32 v2, v2, v89, v108
	v_max3_f32 v3, v3, v110, v111
	v_max3_f32 v2, v2, v109, v92
	v_max3_f32 v3, v3, v94, v95
	v_max3_f32 v2, v2, v93, v3
	v_mov_b32_e32 v3, v2
	s_nop 1
	v_permlane32_swap_b32_e32 v2, v3
	v_max_f32_e32 v2, v2, v3


	s_mov_b32 s20, 0x41000000
	v_cmp_lt_f32_e32 vcc, s20, v2
	s_cmp_lg_u64 vcc, 0

	s_cselect_b64 s[20:21], -1, 0
	s_cbranch_vccnz .LBB0_2000
.LBB0_1993:
	s_waitcnt lgkmcnt(14)
	v_mfma_f32_32x32x16_bf16 v[64:79], v[160:163], v[196:199], v[64:79]
	v_exp_f32_e32 v96, v96
	v_exp_f32_e32 v97, v97
	ds_read_b64_tr_b16 v[2:3], v213 offset:32768
	ds_read_b64_tr_b16 v[4:5], v213 offset:33280
	s_waitcnt lgkmcnt(14)
	v_mfma_f32_32x32x16_bf16 v[48:63], v[160:163], v[192:195], v[48:63]
	v_exp_f32_e32 v98, v98
	v_exp_f32_e32 v99, v99
	ds_read_b64_tr_b16 v[10:11], v213 offset:36864
	ds_read_b64_tr_b16 v[12:13], v213 offset:37376
	v_add_u32_e32 v14, s52, v250
	ds_read_b128 v[204:207], v14
	ds_read_b128 v[196:199], v14 offset:512
	s_waitcnt lgkmcnt(14)
	v_mfma_f32_32x32x16_bf16 v[64:79], v[152:155], v[188:191], v[64:79]
	v_exp_f32_e32 v100, v100
	v_exp_f32_e32 v101, v101
	ds_read_b64_tr_b16 v[116:117], v213 offset:33792
	ds_read_b64_tr_b16 v[118:119], v213 offset:34304
	ds_read_b128 v[200:203], v14 offset:2048
	ds_read_b128 v[192:195], v14 offset:2560
	v_mfma_f32_32x32x16_bf16 v[48:63], v[152:155], v[136:139], v[48:63]
	v_exp_f32_e32 v102, v102
	v_exp_f32_e32 v103, v103
	ds_read_b64_tr_b16 v[120:121], v213 offset:37888
	ds_read_b64_tr_b16 v[122:123], v213 offset:38400
	ds_read_b128 v[188:191], v14 offset:4096
	ds_read_b128 v[184:187], v14 offset:4608
	s_waitcnt lgkmcnt(14)
	v_mfma_f32_32x32x16_bf16 v[64:79], v[148:151], v[132:135], v[64:79]
	v_exp_f32_e32 v104, v104
	v_exp_f32_e32 v105, v105
	ds_read_b64_tr_b16 v[124:125], v213 offset:34816
	ds_read_b64_tr_b16 v[126:127], v213 offset:35328
	ds_read_b128 v[180:183], v14 offset:6144
	ds_read_b128 v[176:179], v14 offset:6656
	v_mfma_f32_32x32x16_bf16 v[48:63], v[148:151], v[128:131], v[48:63]
	v_exp_f32_e32 v106, v106
	v_exp_f32_e32 v107, v107
	ds_read_b64_tr_b16 v[128:129], v213 offset:38912
	ds_read_b64_tr_b16 v[130:131], v213 offset:39424
	v_mfma_f32_32x32x16_bf16 v[64:79], v[144:147], v[112:115], v[64:79]
	v_exp_f32_e32 v108, v108
	v_exp_f32_e32 v109, v109
	ds_read_b64_tr_b16 v[112:113], v213 offset:35840
	ds_read_b64_tr_b16 v[114:115], v213 offset:36352
	v_mfma_f32_32x32x16_bf16 v[48:63], v[144:147], v[6:9], v[48:63]
	v_exp_f32_e32 v110, v110
	v_exp_f32_e32 v111, v111
	ds_read_b64_tr_b16 v[6:7], v213 offset:39936
	ds_read_b64_tr_b16 v[8:9], v213 offset:40448
	s_waitcnt lgkmcnt(14)
	v_mfma_f32_32x32x16_bf16 v[32:47], v[160:163], v[2:5], v[32:47]
	v_exp_f32_e32 v80, v80
	v_exp_f32_e32 v81, v81
	v_mfma_f32_32x32x16_bf16 v[16:31], v[160:163], v[10:13], v[16:31]
	v_exp_f32_e32 v82, v82
	v_exp_f32_e32 v83, v83
	v_mfma_f32_32x32x16_bf16 v[32:47], v[152:155], v[116:119], v[32:47]
	v_exp_f32_e32 v84, v84
	v_exp_f32_e32 v85, v85
	s_waitcnt lgkmcnt(12)
	v_mfma_f32_32x32x16_bf16 v[16:31], v[152:155], v[120:123], v[16:31]
	v_exp_f32_e32 v86, v86
	v_exp_f32_e32 v87, v87
	s_waitcnt lgkmcnt(8)
	v_mfma_f32_32x32x16_bf16 v[32:47], v[148:151], v[124:127], v[32:47]
	v_exp_f32_e32 v88, v88
	v_exp_f32_e32 v89, v89
	s_waitcnt lgkmcnt(4)
	v_mfma_f32_32x32x16_bf16 v[16:31], v[148:151], v[128:131], v[16:31]
	v_exp_f32_e32 v90, v90
	v_exp_f32_e32 v91, v91
	s_waitcnt lgkmcnt(2)
	v_mfma_f32_32x32x16_bf16 v[32:47], v[144:147], v[112:115], v[32:47]
	v_exp_f32_e32 v92, v92
	v_exp_f32_e32 v93, v93
	s_waitcnt lgkmcnt(0)
	v_mfma_f32_32x32x16_bf16 v[16:31], v[144:147], v[6:9], v[16:31]
	v_exp_f32_e32 v94, v94
	v_exp_f32_e32 v95, v95
	s_add_i32 s24, s52, 0x2000
	s_cmpk_lg_i32 s52, 0x4000
	s_cselect_b32 s54, s24, 0
	s_add_u32 s2, s2, 0x40000
	s_addc_u32 s3, s3, 0
	s_add_i32 s24, s28, 2
	s_cmp_ge_u32 s24, s51
	s_cbranch_scc1 .Lrot_exit
	s_mov_b32 s28, s24
	s_lshl_b32 s30, s27, 1
	s_mov_b32 s29, s52
	s_mov_b32 s27, s54
	v_add_u32_e32 v214, s30, v251
	s_waitcnt vmcnt(3) lgkmcnt(0)
	s_barrier
	s_andn2_b64 vcc, exec, s[20:21]
	s_cbranch_vccnz .LBB0_1995
	s_waitcnt lgkmcnt(0)
	ds_read_b128 v[2:5], v0 offset:96
	ds_read_b128 v[6:9], v0 offset:64
	ds_read_b128 v[10:13], v0 offset:32
	ds_read_b128 v[112:115], v0
	s_waitcnt lgkmcnt(3)
	v_mul_f32_e32 v76, v76, v2
	v_mul_f32_e32 v77, v77, v3
	s_waitcnt lgkmcnt(2)
	v_mul_f32_e32 v72, v72, v6
	v_mul_f32_e32 v73, v73, v7
	s_waitcnt lgkmcnt(1)
	v_mul_f32_e32 v68, v68, v10
	v_mul_f32_e32 v69, v69, v11
	v_mul_f32_e32 v78, v78, v4
	v_mul_f32_e32 v79, v79, v5
	v_mul_f32_e32 v74, v74, v8
	v_mul_f32_e32 v75, v75, v9
	v_mul_f32_e32 v70, v70, v12
	v_mul_f32_e32 v71, v71, v13
	s_waitcnt lgkmcnt(0)
	v_mul_f32_e32 v66, v66, v114
	v_mul_f32_e32 v67, v67, v115
	v_mul_f32_e32 v64, v64, v112
	v_mul_f32_e32 v65, v65, v113
	v_mul_f32_e32 v60, v60, v2
	v_mul_f32_e32 v61, v61, v3
	v_mul_f32_e32 v56, v56, v6
	v_mul_f32_e32 v57, v57, v7
	v_mul_f32_e32 v52, v52, v10
	v_mul_f32_e32 v53, v53, v11
	v_mul_f32_e32 v62, v62, v4
	v_mul_f32_e32 v63, v63, v5
	v_mul_f32_e32 v58, v58, v8
	v_mul_f32_e32 v59, v59, v9
	v_mul_f32_e32 v54, v54, v12
	v_mul_f32_e32 v55, v55, v13
	v_mul_f32_e32 v50, v50, v114
	v_mul_f32_e32 v51, v51, v115
	v_mul_f32_e32 v48, v48, v112
	v_mul_f32_e32 v49, v49, v113
	v_mul_f32_e32 v44, v44, v2
	v_mul_f32_e32 v45, v45, v3
	v_mul_f32_e32 v40, v40, v6
	v_mul_f32_e32 v41, v41, v7
	v_mul_f32_e32 v36, v36, v10
	v_mul_f32_e32 v37, v37, v11
	v_mul_f32_e32 v46, v46, v4
	v_mul_f32_e32 v47, v47, v5
	v_mul_f32_e32 v42, v42, v8
	v_mul_f32_e32 v43, v43, v9
	v_mul_f32_e32 v38, v38, v12
	v_mul_f32_e32 v39, v39, v13
	v_mul_f32_e32 v34, v34, v114
	v_mul_f32_e32 v35, v35, v115
	v_mul_f32_e32 v32, v32, v112
	v_mul_f32_e32 v33, v33, v113
	v_mul_f32_e32 v28, v28, v2
	v_mul_f32_e32 v29, v29, v3
	v_mul_f32_e32 v24, v24, v6
	v_mul_f32_e32 v25, v25, v7
	v_mul_f32_e32 v20, v20, v10
	v_mul_f32_e32 v21, v21, v11
	v_mul_f32_e32 v30, v30, v4
	v_mul_f32_e32 v31, v31, v5
	v_mul_f32_e32 v26, v26, v8
	v_mul_f32_e32 v27, v27, v9
	v_mul_f32_e32 v22, v22, v12
	v_mul_f32_e32 v23, v23, v13
	v_mul_f32_e32 v18, v18, v114
	v_mul_f32_e32 v19, v19, v115
	v_mul_f32_e32 v16, v16, v112
	v_mul_f32_e32 v17, v17, v113
.LBB0_1995:

	s_branch .Lrot_body2
